# GLA scan prologue/epilogue trimming: six dead k/V tile loads of the compiled prologue dropped; the barrier ending the scan waits for LDS traffic only
# speedup vs baseline: 1.0112x; 1.0014x over previous
; __device__ __forceinline__ unsigned pk2(float lo, float hi) { f32x2_t v = {lo, hi}; bf16x2_t b = __builtin_convertvector(v, bf16x2_t); return __builtin_bit_cast(unsigned, b); }
; __device__ __forceinline__ void scan_unit(const int unit, const Args& a, unsigned char* lds, const int mk_wid) {
;     ...
;     { const int l_ = MK_TID & 63, r32 = l_ & 31, hi = l_ >> 5; const float* up = a.in[dir ? 12 : 10] + (size_t)(8 * hi) * 512 + h * 128 + (wid & 3) * 32 + r32;
;       v4u w; w.x = pk2(up[0], up[512]); w.y = pk2(up[2 * 512], up[3 * 512]); w.z = pk2(up[4 * 512], up[5 * 512]); w.w = pk2(up[6 * 512], up[7 * 512]);
;       upf = __builtin_bit_cast(bf16x8, w); biasc = a.in[dir ? 13 : 11][h * 128 + (wid & 3) * 32 + r32]; }
;     u16* qe = (u16*)(lds + L_QE); u16* ke = (u16*)(lds + L_KE); u16* am = (u16*)(lds + L_AM);
;     float* las = (float*)(lds + L_LAS); float* gs = (float*)(lds + L_GS); float* dl = (float*)(lds + L_DL);
;     const int ldsb = (int)(uintptr_t)lds;
;     u16* ot = (u16*)(lds + L_LAS);
;     int pend_cc = -1;
;     ...
;     f32x16 S[4]; S[0] = f32x16{}; S[1] = f32x16{}; S[2] = f32x16{}; S[3] = f32x16{};
;     bf16x8 qraw[2], kraw[2], vraw[4]; bf16x8 lraw = bf16x8{};
;     ...
;     GLA_LOAD(0);
.LBB0_410:
	s_andn2_b64 vcc, exec, s[4:5]
	s_cbranch_vccnz .LBB0_450
	s_and_b64 vcc, exec, s[2:3]
	s_cbranch_vccnz .LBB0_450
	s_and_b32 s9, s8, 1
	s_bfe_i32 s20, s8, 0x10000
	s_bfe_u32 s22, s8, 0x20001
	s_ashr_i32 s18, s8, 3
	s_bitcmp1_b32 s8, 0
	s_cselect_b64 s[6:7], -1, 0
	s_cmp_eq_u32 s9, 0
	s_mov_b32 s5, 0
	s_cselect_b64 s[2:3], -1, 0
	s_movk_i32 s4, 0x50
	s_and_b64 s[12:13], s[2:3], exec
	s_cselect_b32 s4, s4, 0x60
	s_movk_i32 s12, 0x58
	s_cselect_b32 s15, s12, 0x68
	s_add_u32 s12, s0, s4
	s_addc_u32 s13, s1, 0
	v_mbcnt_lo_u32_b32 v0, -1, 0
	v_mbcnt_hi_u32_b32 v0, -1, v0
	s_load_dwordx2 s[12:13], s[12:13], 0x0
	s_bfe_u32 s26, s33, 0x20006
	s_lshl_b32 s27, s22, 7
	s_lshl_b32 s4, s22, 9
	s_lshl_b32 s34, s26, 5
	s_lshl_b32 s14, s26, 7
	v_and_b32_e32 v14, 31, v0
	v_lshlrev_b32_e32 v0, 9, v0
	v_mov_b32_e32 v96, 0
	s_add_u32 s16, s0, s15
	v_and_b32_e32 v0, 0x4000, v0
	v_mov_b32_e32 v1, v96
	s_addc_u32 s17, s1, 0
	s_load_dwordx2 s[16:17], s[16:17], 0x0
	s_waitcnt lgkmcnt(0)
	v_lshl_add_u64 v[0:1], s[12:13], 0, v[0:1]
	v_lshl_add_u64 v[0:1], v[0:1], 0, s[4:5]
	s_mov_b32 s15, s5
	v_lshl_add_u64 v[0:1], v[0:1], 0, s[14:15]
	v_lshlrev_b32_e32 v2, 2, v14
	v_mov_b32_e32 v3, v96
	v_lshl_add_u64 v[0:1], v[0:1], 0, v[2:3]
	s_movk_i32 s12, 0x1000
	v_add_co_u32_e32 v10, vcc, s12, v0
	s_movk_i32 s12, 0x2000
	s_nop 0
	v_addc_co_u32_e32 v11, vcc, 0, v1, vcc
	v_add_co_u32_e32 v6, vcc, s12, v0
	s_movk_i32 s12, 0x3000
	s_nop 0
	v_addc_co_u32_e32 v7, vcc, 0, v1, vcc
	v_add_co_u32_e32 v12, vcc, s12, v0
	s_or_b32 s12, s34, s27
	global_load_dword v2, v[6:7], off offset:-4096
	global_load_dword v3, v[6:7], off
	global_load_dword v4, v[6:7], off offset:2048
	v_addc_co_u32_e32 v13, vcc, 0, v1, vcc
	global_load_dword v5, v[0:1], off
	global_load_dword v7, v[0:1], off offset:2048
	global_load_dword v8, v[10:11], off offset:2048
	global_load_dword v6, v[12:13], off
	global_load_dword v9, v[12:13], off offset:2048
	v_or_b32_e32 v0, s12, v14
	v_lshlrev_b32_e32 v0, 2, v0
	global_load_dword v156, v0, s[16:17]
	v_mbcnt_lo_u32_b32 v0, -1, 0
	v_mbcnt_hi_u32_b32 v0, -1, v0
	s_mul_hi_i32 s13, s18, 0x900
	v_add_u32_e32 v10, s72, v0
	s_mul_i32 s12, s18, 0x900
	s_and_b32 s14, s20, 0xc0
	s_ashr_i32 s19, s18, 31
	s_or_b64 s[20:21], s[12:13], s[14:15]
	v_ashrrev_i32_e32 v11, 4, v10
	s_lshl_b32 s35, s22, 8
	s_add_u32 s14, s38, s35
	v_sub_u32_e32 v12, 63, v11
	s_addc_u32 s15, s39, 0
	v_cndmask_b32_e64 v12, v12, v11, s[2:3]
	v_add_u32_e32 v14, 32, v11
	v_sub_u32_e32 v11, 31, v11
	s_add_u32 s14, s14, 0xfa00000
	v_lshlrev_b32_e32 v16, 4, v10
	v_ashrrev_i32_e32 v13, 31, v12
	v_cndmask_b32_e64 v14, v11, v14, s[2:3]
	s_addc_u32 s15, s15, 0
	v_and_b32_e32 v0, 0xf0, v16
	v_mov_b32_e32 v1, v96
	v_lshl_add_u64 v[12:13], s[20:21], 0, v[12:13]
	v_ashrrev_i32_e32 v15, 31, v14
	v_lshl_add_u64 v[0:1], s[14:15], 0, v[0:1]
	v_lshlrev_b64 v[12:13], 10, v[12:13]
	v_lshl_add_u64 v[14:15], s[20:21], 0, v[14:15]
	s_add_u32 s24, s38, 0x1a600000
	v_lshl_add_u64 v[12:13], v[0:1], 0, v[12:13]
	v_lshlrev_b64 v[14:15], 10, v[14:15]
	s_addc_u32 s25, s39, 0
	v_ashrrev_i32_e32 v11, 5, v10
	v_lshl_add_u64 v[0:1], v[0:1], 0, v[14:15]
	s_add_u32 s4, s38, s4
	v_sub_u32_e32 v12, 63, v11
	s_addc_u32 s17, s39, 0
	v_cndmask_b32_e64 v12, v12, v11, s[2:3]
	v_add_u32_e32 v14, 16, v11
	v_sub_u32_e32 v15, 47, v11
	s_add_u32 s16, s4, 0x11e00000
	v_ashrrev_i32_e32 v13, 31, v12
	v_cndmask_b32_e64 v14, v15, v14, s[2:3]
	s_addc_u32 s17, s17, 0
	v_and_b32_e32 v0, 0x1f0, v16
	v_mov_b32_e32 v1, v96
	v_lshl_add_u64 v[12:13], s[20:21], 0, v[12:13]
	v_ashrrev_i32_e32 v15, 31, v14
	v_lshl_add_u64 v[0:1], s[16:17], 0, v[0:1]
	v_lshlrev_b64 v[12:13], 11, v[12:13]
	v_lshl_add_u64 v[14:15], s[20:21], 0, v[14:15]
	v_lshl_add_u64 v[12:13], v[0:1], 0, v[12:13]
	v_lshlrev_b64 v[14:15], 11, v[14:15]
	v_lshl_add_u64 v[14:15], v[0:1], 0, v[14:15]
	v_add_u32_e32 v12, 32, v11
	v_sub_u32_e32 v13, 31, v11
	v_cndmask_b32_e64 v12, v13, v12, s[2:3]
	v_add_u32_e32 v14, 48, v11
	v_sub_u32_e32 v11, 15, v11
	v_ashrrev_i32_e32 v13, 31, v12
	v_cndmask_b32_e64 v14, v11, v14, s[2:3]
	v_lshl_add_u64 v[12:13], s[20:21], 0, v[12:13]
	v_ashrrev_i32_e32 v15, 31, v14
	v_lshlrev_b64 v[12:13], 11, v[12:13]
	v_lshl_add_u64 v[14:15], s[20:21], 0, v[14:15]
	v_lshl_add_u64 v[12:13], v[0:1], 0, v[12:13]
	v_lshlrev_b64 v[14:15], 11, v[14:15]
	v_lshl_add_u64 v[0:1], v[0:1], 0, v[14:15]
	s_movk_i32 s4, 0x7f
	v_cmp_lt_i32_e32 vcc, s4, v10
	s_and_saveexec_b64 s[22:23], vcc
	s_xor_b64 s[22:23], exec, s[22:23]
	s_lshl_b32 s4, s9, 4
	s_or_saveexec_b64 s[22:23], s[22:23]
	v_mov_b32_e32 v97, v96
	v_mov_b32_e32 v98, v96
	v_mov_b32_e32 v99, v96
	v_mov_b64_e32 v[0:1], s[4:5]
	s_xor_b64 exec, exec, s[22:23]
	s_cbranch_execz .LBB0_416
	v_ashrrev_i32_e32 v0, 1, v10
	v_sub_u32_e32 v1, 63, v0
	v_cndmask_b32_e64 v0, v1, v0, s[2:3]
	v_ashrrev_i32_e32 v1, 31, v0
	v_lshl_add_u64 v[0:1], s[20:21], 0, v[0:1]
	v_lshlrev_b32_e32 v11, 3, v10
	v_lshlrev_b64 v[0:1], 6, v[0:1]
	s_mov_b32 s21, 0
	v_lshl_add_u64 v[0:1], s[24:25], 0, v[0:1]
	s_lshl_b32 s42, s9, 5
	s_mov_b32 s43, s21
	v_and_b32_e32 v10, 8, v11
	v_lshl_add_u64 v[0:1], v[0:1], 0, s[42:43]
	v_lshlrev_b32_e32 v10, 1, v10
	v_mov_b32_e32 v11, 0
	v_lshl_add_u64 v[0:1], v[0:1], 0, v[10:11]
	global_load_dwordx4 v[96:99], v[0:1], off
	s_lshl_b32 s20, s9, 4
	v_mov_b64_e32 v[0:1], s[20:21]

; __global__ void __launch_bounds__(512) mk_fwd(Args a) {
;     ...
;         const att::bf16* Qp = (const att::bf16*)(ws + WS_Q); const att::bf16* Kp = (const att::bf16*)(ws + WS_K); const att::bf16* Vp = (const att::bf16*)(ws + WS_V);
;         const float* rope = (const float*)(ws + WS_ROPE);
;         const bool full = (G == 256);
;         if (full) { if (bx < 128) gla::scan_unit(bx, a, lds, mk_wid); }
;         else { for (int u = bx; u < 128; u += G) gla::scan_unit(u, a, lds, mk_wid); }
;         __syncthreads();
;         const int xj = bx >> 3, xx = bx & 7;
;         const int nun = full ? (xj < 16 ? 3 : 5) : 0;
;         for (int i = 0; ; ++i) {
;             int bk, w;
;             if (full) { if (i >= nun) break; const int idx = (xj < 16) ? 80 + i * 16 + xj : i * 16 + (xj - 16); bk = (idx >> 5) * 8 + xx; w = idx & 31; }
;             else { const int u = i * G + bx; if (u >= 1024) break; bk = u >> 5; w = u & 31; }
;             const int b = bk >> 1, kvh = bk & 1, hq = kvh * 4 + (w >> 3), qb = w & 7;
;             const size_t qoff = ((size_t)b * T + (size_t)qb * 256) * 1024 + hq * 128;
;             const size_t koff = (size_t)b * TA * 256 + kvh * 128;
;             att::attn_unit(Qp + qoff, Kp + koff, Vp + koff, (att::bf16*)(ws + WS_Q) + qoff, TA, (char*)lds, rope + (size_t)qb * 256 * 128, a.in[8], mk_wid);
.LBB0_450:
	s_add_u32 s9, s38, 0x7200000
	s_addc_u32 s47, s39, 0
	s_add_u32 s60, s38, 0xb200000
	s_addc_u32 s61, s39, 0
	s_add_u32 s62, s38, 0xc400000
	s_addc_u32 s63, s39, 0
	s_add_u32 s64, s38, 0x200000
	s_addc_u32 s65, s39, 0
	s_lshl_b32 s2, s72, 2
	s_mov_b32 s12, 0
	s_add_i32 s67, s2, 0
	s_lshl_b32 s6, s70, 5
	s_lshl_b32 s2, s70, 13
	s_mov_b32 s7, s12
	s_ashr_i32 s69, s8, 3
	s_and_b32 s66, s8, 7
	s_add_i32 s67, s67, 0x10000
	s_add_i32 s68, s2, 0
	s_lshl_b64 s[34:35], s[6:7], 11
	s_cmp_lt_i32 s69, 16
	s_load_dwordx2 s[42:43], s[0:1], 0x40
	s_cselect_b32 s2, 0x50, -16
	s_cselect_b32 s7, 3, 5
	s_add_i32 s69, s69, s2
	s_add_u32 s44, s38, 0xc424000
	s_addc_u32 s45, s39, 0
	v_mov_b32_e32 v177, 0
	v_mov_b32_e32 v180, 0x358637bd
	s_mov_b32 s73, 0x800000
	s_mov_b32 s74, 0x42b504f3
	s_mov_b32 s46, 0x3e0293ee
	s_mov_b64 s[48:49], 0x8000
	s_mov_b64 s[50:51], 0xc000
	s_mov_b64 s[52:53], 0x10000
	s_mov_b64 s[54:55], 0x14000
	s_mov_b32 s75, 0xffff4000
	s_movk_i32 s76, 0x8000
	s_mov_b32 s77, 0xfedf4000
	s_mov_b32 s78, 0xfedf8000
	v_mov_b32_e32 v181, 0xf149f2ca
	v_mov_b32_e32 v182, 0x120000
	s_mov_b32 s79, 0
	s_waitcnt lgkmcnt(0)
	s_barrier
	s_cmp_lt_u32 s70, 4
	s_cbranch_scc0 .Lattn_prio_done
	s_setprio 1
